# phase15 NSA sel/window loop: LDS-DMA 4-stage ring for K/V tiles, hand-scheduled fast path for unmasked tiles, half-iteration stagger of waves 4-7
# speedup vs baseline: 1.0381x; 1.0381x over previous
; __device__ __forceinline__ int rho_row(int k) { return (k & 32) | ((k & 4) << 2) | ((k & 24) >> 1) | (k & 3); }
; __device__ __forceinline__ void phase_nsa_sw(const Params& p, u16* sm) {
;   const int tid = threadIdx.x, lane = tid & 63, wave = tid >> 6, fr = lane & 15, fq = lane >> 4;
;   const int wq = wave & 3, qh = wave >> 2;
;   u16* sK = sm; u16* sV = sm + 64 * LDSP;
;   int* lst = (int*)(sm + 4 * 64 * LDSP);
;   uint2* selL = (uint2*)(sm + 4 * 64 * LDSP + 256) + wave * 512 + lane;
;   const int ntiles = 16 * 128;
;     ...
;     const int pc = tid & 7, pr = tid >> 3, prl = rho_row(pr);
;     uint4 rkA, rvA;
.LBB0_1319:
	s_cmp_lt_i32 s74, 16
	s_cselect_b64 s[0:1], -1, 0
	s_cmp_gt_i32 s75, 14
	s_cselect_b64 s[4:5], -1, 0
	s_and_b64 s[0:1], s[0:1], s[4:5]
	s_andn2_b64 vcc, exec, s[0:1]
	s_cbranch_vccnz .LBB0_1406
	s_cmpk_gt_i32 s2, 0x7ff
	s_cbranch_scc1 .LBB0_1362
	s_load_dword s0, s[96:97], 0xb0
	v_lshlrev_b64 v[2:3], v192, -1
	v_and_b32_e32 v5, 15, v192
	v_lshrrev_b32_e32 v4, 4, v192
	v_not_b32_e32 v173, v3
	v_not_b32_e32 v178, v2
	v_lshrrev_b32_e32 v3, 3, v192
	v_lshrrev_b32_e32 v2, 1, v192
	v_and_b32_e32 v0, 63, v192
	v_and_or_b32 v172, v4, 48, v5
	v_and_b32_e32 v2, 16, v2
	v_and_b32_e32 v4, 12, v4
	v_and_b32_e32 v6, 35, v3
	v_lshlrev_b32_e32 v1, 6, v192
	v_lshlrev_b32_e32 v0, 3, v0
	s_mov_b32 s1, 0xf000
	s_waitcnt lgkmcnt(0)
	s_cmpk_eq_i32 s0, 0x100
	v_or3_b32 v7, v4, v6, v2
	v_lshlrev_b32_e32 v4, 3, v192
	v_and_or_b32 v179, v1, s1, v0
	v_bfe_u32 v1, v192, 4, 2
	s_cselect_b64 s[6:7], -1, 0
	v_lshrrev_b32_e32 v0, 5, v192
	v_and_b32_e32 v4, 56, v4
	v_and_b32_e32 v212, 6, v0
	v_lshlrev_b32_e32 v174, 3, v1
	v_mov_b32_e32 v0, 0
	v_lshlrev_b32_e32 v2, 7, v3
	v_lshlrev_b32_e32 v6, 12, v3
	v_lshlrev_b32_e32 v8, 1, v4
	s_movk_i32 s8, 0x90
	v_lshlrev_b32_e32 v10, 2, v1
	v_cndmask_b32_e64 v1, 0, 1, s[6:7]
	s_ashr_i32 s1, s2, 4
	v_mov_b32_e32 v175, v0
	v_mad_u32_u24 v215, v7, s8, v8
	v_mad_u32_u24 v216, v3, s8, v8
	v_and_b32_e32 v8, 48, v192
	v_mul_u32_u24_e32 v217, 0x48, v5
	v_mov_b32_e32 v9, v0
	v_cmp_ne_u32_e64 s[6:7], 1, v1
	v_lshlrev_b32_e32 v186, 1, v2
	v_lshlrev_b32_e32 v188, 1, v4
	v_lshlrev_b32_e32 v190, 1, v6
	v_mbcnt_lo_u32_b32 v1, -1, 0
	s_sub_i32 s46, 31, s1
	v_cmp_gt_u32_e64 s[4:5], 64, v192
	v_lshlrev_b64 v[176:177], v192, 1
	v_lshlrev_b32_e32 v213, 2, v192
	v_add_u32_e32 v214, 64, v192
	v_lshl_add_u32 v218, v217, 1, v8
	v_not_b32_e32 v219, v174
	v_lshl_add_u64 v[180:181], s[52:53], 0, v[8:9]
	v_lshl_add_u64 v[182:183], s[64:65], 0, v[174:175]
	s_mov_b32 s43, 0
	s_movk_i32 s47, 0xc0
	v_mov_b64_e32 v[184:185], s[80:81]
	v_lshlrev_b32_e32 v175, 3, v172
	s_mov_b32 s60, 0xf149f2ca
	s_mov_b32 s48, 0x3f803f80
	v_lshlrev_b32_e32 v194, 1, v10
	v_mov_b32_e32 v196, v186
	v_mov_b32_e32 v197, v0
	v_mov_b32_e32 v198, v188
	v_mov_b32_e32 v199, v0
	v_mov_b32_e32 v200, v190
	v_mov_b32_e32 v201, v0
	v_mbcnt_hi_u32_b32 v220, -1, v1
	v_mov_b32_e32 v221, 0xf149f2ca
	v_mov_b32_e32 v222, 0x80
	v_mov_b32_e32 v223, 0x100
	v_mov_b32_e32 v224, 0x200
	v_mov_b32_e32 v225, 0x400
	v_mov_b32_e32 v226, 0x800
	v_mov_b32_e32 v227, 0x1000
	v_mov_b32_e32 v228, 0x2000
	v_mov_b32_e32 v229, 0x4000
	v_mov_b32_e32 v230, 0x8000
	v_and_b32_e32 v236, 63, v192
	v_lshrrev_b32_e32 v237, 6, v192
	v_mul_u32_u24_e32 v238, 0x1c72, v192
	v_lshrrev_b32_e32 v238, 16, v238
	v_mul_u32_u24_e32 v239, 9, v238
	v_sub_u32_e32 v239, v192, v239
	v_min_u32_e32 v239, 7, v239
	v_lshlrev_b32_e32 v239, 4, v239
	v_lshl_add_u32 v249, v238, 13, v239
	v_and_b32_e32 v240, 35, v238
	v_and_b32_e32 v241, 16, v238
	v_lshrrev_b32_e32 v241, 2, v241
	v_and_b32_e32 v242, 12, v238
	v_lshlrev_b32_e32 v242, 1, v242
	v_or3_b32 v240, v240, v241, v242
	v_lshl_add_u32 v248, v240, 8, v239
	v_lshlrev_b32_e32 v251, 10, v237
	v_and_b32_e32 v240, 3, v237
	v_lshrrev_b32_e32 v241, 2, v237
	v_and_b32_e32 v236, 15, v236
	v_lshl_add_u32 v242, v240, 4, v236
	v_add_u32_e32 v242, 0x200, v242
	v_mul_u32_u24_e32 v238, 0x1c72, v242
	v_lshrrev_b32_e32 v238, 16, v238
	v_mul_u32_u24_e32 v239, 9, v238
	v_sub_u32_e32 v239, v242, v239
	v_min_u32_e32 v239, 7, v239
	v_lshlrev_b32_e32 v239, 4, v239
	v_lshl_add_u32 v243, v238, 13, v239
	v_and_b32_e32 v244, 35, v238
	v_and_b32_e32 v245, 16, v238
	v_lshrrev_b32_e32 v245, 2, v245
	v_and_b32_e32 v246, 12, v238
	v_lshlrev_b32_e32 v246, 1, v246
	v_or3_b32 v244, v244, v245, v246
	v_lshl_add_u32 v244, v244, 8, v239
	v_cmp_ne_u32_e32 vcc, 0, v241
	v_mul_u32_u24_e32 v252, 0x2400, v241
	v_lshl_add_u32 v252, v240, 8, v252
	v_add_u32_e32 v252, 0x2000, v252
	v_cndmask_b32_e32 v250, v244, v243, vcc
	s_mov_b32 s61, s2
	s_branch .LBB0_1324

; __device__ __forceinline__ int rho_row(int k) { return (k & 32) | ((k & 4) << 2) | ((k & 24) >> 1) | (k & 3); }
; #define NSA_FETCH(rk, rv, e) do { const int v_ = lst[(e)]; \
;       const u16* kp_ = (v_ < 64) ? ksb + (size_t)v_ * 64 * 128 : kwb + (size_t)(v_ - 64) * 64 * 128; \
;       const u16* vp_ = (v_ < 64) ? vsb + v_ * 64 : vwb + (v_ - 64) * 64; \
;       rk = *(const uint4*)(kp_ + (size_t)pr * 128 + pc * 8); rv = *(const uint4*)(vp_ + (size_t)pr * SEQ + pc * 8); } while (0)
; #define NSA_PUT(rk, rv, buf) do { *(uint4*)(sK + (buf) * 2 * 64 * LDSP + prl * LDSP + pc * 8) = rk; \
;       *(uint4*)(sV + (buf) * 2 * 64 * LDSP + pr * LDSP + pc * 8) = rv; } while (0)
; __device__ __forceinline__ void phase_nsa_sw(const Params& p, u16* sm) {
;     ...
;     const u16* ksb = p.ksb + tokbase * 128 + g * 64;
;     const u16* vsb = p.vsT + (size_t)(b * 2 + g) * 64 * SEQ;
;     const u16* kwb = p.kwb + tokbase * 128 + g * 64;
;     const u16* vwb = p.vwT + (size_t)(b * 2 + g) * 64 * SEQ;
;     const int kt_lo = (t0 >= 511) ? ((t0 - 511) >> 6) : 0, kt_hi = (t0 + 31) >> 6;
;     const int nsel = __popcll(um), ntl = nsel + (kt_hi - kt_lo + 1);
;     if (tid < 64) {
;       if ((um >> tid) & 1ull) lst[__popcll(um & ((1ull << tid) - 1ull))] = tid;
;       if (tid <= kt_hi - kt_lo) lst[nsel + tid] = 64 + kt_lo + tid;
;     }
;     __syncthreads();
;     const int pc = tid & 7, pr = tid >> 3, prl = rho_row(pr);
;     uint4 rkA, rvA;
;     ...
;     NSA_FETCH(rkA, rvA, 0);
;     NSA_PUT(rkA, rvA, 0);
;     if (ntl > 1) NSA_FETCH(rkA, rvA, 1);
.LBB0_1332:
	s_or_b64 exec, exec, s[8:9]
	s_lshl_b32 s8, s42, 8
	s_add_u32 s9, s3, s8
	s_addc_u32 s10, s76, 0
	s_lshl_b32 s11, s12, 7
	s_add_u32 s62, s9, s11
	s_addc_u32 s63, s10, 0
	s_lshl_b32 s9, s13, 19
	s_add_u32 s66, s85, s9
	s_addc_u32 s67, s86, 0
	s_waitcnt lgkmcnt(0)
	s_barrier
	s_add_u32 s8, s77, s8
	s_addc_u32 s10, s84, 0
	s_add_u32 s78, s8, s11
	s_addc_u32 s79, s10, 0
	s_add_u32 s80, s87, s9
	s_addc_u32 s81, s88, 0
	v_add_u32_e32 v1, s14, v203
	v_add_u32_e32 v231, 1, v1
	v_and_b32_e32 v3, 63, v192
	v_lshlrev_b32_e32 v3, 2, v3
	ds_read_b32 v24, v3 offset:36864
	ds_read_b32 v25, v3 offset:37120
	v_readfirstlane_b32 s13, v1
	v_mov_b32_e32 v20, s48
	v_mov_b32_e32 v21, s48
	v_mov_b32_e32 v22, s48
	v_mov_b32_e32 v23, s48
	s_min_i32 s9, s13, 1
	s_min_i32 s10, s13, 2
	s_waitcnt lgkmcnt(0)
	v_readlane_b32 s8, v24, 0
	v_readlane_b32 s9, v24, s9
	v_readlane_b32 s10, v24, s10
	s_mov_b32 s12, 0
	s_cmp_lt_i32 s8, 64
	s_cselect_b32 s14, s62, s78
	s_cselect_b32 s15, s63, s79
	s_cselect_b32 s16, s66, s80
	s_cselect_b32 s17, s67, s81
	s_and_b32 s13, s8, 63
	s_lshl_b32 s18, s13, 14
	s_lshl_b32 s13, s13, 7
	s_add_u32 s14, s14, s18
	s_addc_u32 s15, s15, 0
	s_add_u32 s16, s16, s13
	s_addc_u32 s17, s17, 0
	v_readfirstlane_b32 s18, v251
	v_readfirstlane_b32 s19, v252
	s_nop 0
	s_add_u32 s18, s18, s12
	s_mov_b32 m0, s18
	s_add_u32 s18, s18, 0x2400
	global_load_lds_dwordx4 v248, s[14:15]
	s_mov_b32 m0, s18
	s_cmp_ge_u32 s19, 0x2400
	global_load_lds_dwordx4 v249, s[16:17]
	s_cselect_b32 s14, s16, s14
	s_cselect_b32 s15, s17, s15
	s_add_u32 s19, s19, s12
	s_mov_b32 m0, s19
	s_mov_b64 exec, 0xffff
	global_load_lds_dwordx4 v250, s[14:15]
	s_mov_b64 exec, -1
	s_movk_i32 s12, 0x4800
	s_cmp_lt_i32 s9, 64
	s_cselect_b32 s14, s62, s78
	s_cselect_b32 s15, s63, s79
	s_cselect_b32 s16, s66, s80
	s_cselect_b32 s17, s67, s81
	s_and_b32 s13, s9, 63
	s_lshl_b32 s18, s13, 14
	s_lshl_b32 s13, s13, 7
	s_add_u32 s14, s14, s18
	s_addc_u32 s15, s15, 0
	s_add_u32 s16, s16, s13
	s_addc_u32 s17, s17, 0
	v_readfirstlane_b32 s18, v251
	v_readfirstlane_b32 s19, v252
	s_nop 0
	s_add_u32 s18, s18, s12
	s_mov_b32 m0, s18
	s_add_u32 s18, s18, 0x2400
	global_load_lds_dwordx4 v248, s[14:15]
	s_mov_b32 m0, s18
	s_cmp_ge_u32 s19, 0x2400
	global_load_lds_dwordx4 v249, s[16:17]
	s_cselect_b32 s14, s16, s14
	s_cselect_b32 s15, s17, s15
	s_add_u32 s19, s19, s12
	s_mov_b32 m0, s19
	s_mov_b64 exec, 0xffff
	global_load_lds_dwordx4 v250, s[14:15]
	s_mov_b64 exec, -1
	s_mov_b32 s12, 0x12000
	s_cmp_lt_i32 s10, 64
	s_cselect_b32 s14, s62, s78
	s_cselect_b32 s15, s63, s79
	s_cselect_b32 s16, s66, s80
	s_cselect_b32 s17, s67, s81
	s_and_b32 s13, s10, 63
	s_lshl_b32 s18, s13, 14
	s_lshl_b32 s13, s13, 7
	s_add_u32 s14, s14, s18
	s_addc_u32 s15, s15, 0
	s_add_u32 s16, s16, s13
	s_addc_u32 s17, s17, 0
	v_readfirstlane_b32 s18, v251
	v_readfirstlane_b32 s19, v252
	s_nop 0
	s_add_u32 s18, s18, s12
	s_mov_b32 m0, s18
	s_add_u32 s18, s18, 0x2400
	global_load_lds_dwordx4 v248, s[14:15]
	s_mov_b32 m0, s18
	s_cmp_ge_u32 s19, 0x2400
	global_load_lds_dwordx4 v249, s[16:17]
	s_cselect_b32 s14, s16, s14
	s_cselect_b32 s15, s17, s15
	s_add_u32 s19, s19, s12
	s_mov_b32 m0, s19
	s_mov_b64 exec, 0xffff
	global_load_lds_dwordx4 v250, s[14:15]
	s_mov_b64 exec, -1

; __device__ __forceinline__ uint2 pack4(f32x4 v) { return make_uint2(pack2(v[0], v[1]), pack2(v[2], v[3])); }
; __device__ __forceinline__ void phase_nsa_sw(const Params& p, u16* sm) {
;     ...
;     for (int i = 0; i < ntl; ++i) {
;       __syncthreads();
;       const int v = lst[i];
;       const u16* cK = sK + (i & 1) * 2 * 64 * LDSP;
;       const u16* cV = sV + (i & 1) * 2 * 64 * LDSP;
;       if (i == nsel) {
;         f32x4 tmp[2][4];
; #pragma unroll
;         for (int hh = 0; hh < 2; ++hh)
; #pragma unroll
;           for (int dm = 0; dm < 4; ++dm) tmp[hh][dm] = (f32x4){0.f, 0.f, 0.f, 0.f};
;         const float gg[2] = {gates[0][1], gates[1][1]};
;         nsa_finish(st, tmp, gg);
; #pragma unroll
;         for (int hh = 0; hh < 2; ++hh)
; #pragma unroll
;           for (int dm = 0; dm < 4; ++dm) selL[(hh * 4 + dm) * 64] = pack4(tmp[hh][dm]);
;         nsa_reset(st);
;       }
;       nsa_qk(s, cK, qf, fr, fq);
;       {
;         const bool is_sel = (v < 64);
;         const int kt = is_sel ? v : v - 64;
;         const bool lv = is_sel ? (bool)((mymask >> v) & 1ull) : true;
;         const bool masked = is_sel ? (v == (t0 >> 6)) : !((64 * kt + 63 <= t0) && (64 * kt >= t0 - 480));
;         if (masked) {
.LBB0_1336:
	s_waitcnt vmcnt(6)
	s_waitcnt lgkmcnt(0)
	s_barrier
	v_readlane_b32 s14, v24, s42
	v_readlane_b32 s15, v25, s42
	v_cmp_ne_u32_e32 vcc, s42, v203
	s_cmp_lt_u32 s42, 64
	s_cselect_b32 s14, s14, s15
	s_cbranch_vccnz .Lfp15_dispatch
.Lfp15_park:
	v_div_scale_f32 v1, s[8:9], v48, v48, v208
	v_rcp_f32_e32 v2, v1
	v_div_scale_f32 v3, vcc, v208, v48, v208
	v_div_scale_f32 v44, s[8:9], v132, v132, v206
	v_fma_f32 v28, -v1, v2, 1.0
	v_fmac_f32_e32 v2, v28, v2
	v_mul_f32_e32 v28, v3, v2
	v_fma_f32 v29, -v1, v28, v3
	v_rcp_f32_e32 v45, v44
	v_fmac_f32_e32 v28, v29, v2
	v_fma_f32 v1, -v1, v28, v3
	v_div_fmas_f32 v1, v1, v2, v28
	v_div_fixup_f32 v1, v1, v48, v208
	v_cmp_lt_f32_e32 vcc, 0, v48
	v_fma_f32 v46, -v44, v45, 1.0
	v_fmac_f32_e32 v45, v46, v45
	v_cndmask_b32_e32 v28, 0, v1, vcc
	v_div_scale_f32 v46, vcc, v206, v132, v206
	v_mul_f32_e32 v47, v46, v45
	v_fma_f32 v48, -v44, v47, v46
	v_fmac_f32_e32 v47, v48, v45
	v_fma_f32 v44, -v44, v47, v46
	v_div_fmas_f32 v44, v44, v45, v47
	v_pk_fma_f32 v[30:31], v[54:55], v[28:29], 0 op_sel_hi:[1,0,0]
	v_pk_fma_f32 v[32:33], v[52:53], v[28:29], 0 op_sel_hi:[1,0,0]
	v_pk_fma_f32 v[34:35], v[58:59], v[28:29], 0 op_sel_hi:[1,0,0]
	v_pk_fma_f32 v[36:37], v[56:57], v[28:29], 0 op_sel_hi:[1,0,0]
	v_div_fixup_f32 v44, v44, v132, v206
	v_cmp_lt_f32_e32 vcc, 0, v132
	v_pk_fma_f32 v[38:39], v[62:63], v[28:29], 0 op_sel_hi:[1,0,0]
	v_pk_fma_f32 v[40:41], v[60:61], v[28:29], 0 op_sel_hi:[1,0,0]
	v_pk_fma_f32 v[42:43], v[66:67], v[28:29], 0 op_sel_hi:[1,0,0]
	v_pk_fma_f32 v[28:29], v[64:65], v[28:29], 0 op_sel_hi:[1,0,0]
	v_cndmask_b32_e32 v44, 0, v44, vcc
	v_cvt_pk_bf16_f32 v32, v32, v33
	v_cvt_pk_bf16_f32 v33, v30, v31
	v_cvt_pk_bf16_f32 v30, v36, v37
	v_cvt_pk_bf16_f32 v31, v34, v35
	v_pk_fma_f32 v[46:47], v[118:119], v[44:45], 0 op_sel_hi:[1,0,0]
	v_pk_fma_f32 v[48:49], v[116:117], v[44:45], 0 op_sel_hi:[1,0,0]
	v_pk_fma_f32 v[50:51], v[114:115], v[44:45], 0 op_sel_hi:[1,0,0]
	v_pk_fma_f32 v[52:53], v[112:113], v[44:45], 0 op_sel_hi:[1,0,0]
	ds_write2st64_b64 v179, v[32:33], v[30:31] offset0:73 offset1:74
	v_cvt_pk_bf16_f32 v30, v40, v41
	v_cvt_pk_bf16_f32 v31, v38, v39
	v_cvt_pk_bf16_f32 v28, v28, v29
	v_cvt_pk_bf16_f32 v29, v42, v43
	v_pk_fma_f32 v[54:55], v[110:111], v[44:45], 0 op_sel_hi:[1,0,0]
	v_pk_fma_f32 v[56:57], v[108:109], v[44:45], 0 op_sel_hi:[1,0,0]
	v_pk_fma_f32 v[58:59], v[106:107], v[44:45], 0 op_sel_hi:[1,0,0]
	v_pk_fma_f32 v[44:45], v[104:105], v[44:45], 0 op_sel_hi:[1,0,0]
	ds_write2st64_b64 v179, v[30:31], v[28:29] offset0:75 offset1:76
	v_cvt_pk_bf16_f32 v28, v48, v49
	v_cvt_pk_bf16_f32 v29, v46, v47
	v_cvt_pk_bf16_f32 v30, v52, v53
	v_cvt_pk_bf16_f32 v31, v50, v51
	v_mov_b32_e32 v2, v0
	v_mov_b32_e32 v3, v0
	ds_write2st64_b64 v179, v[28:29], v[30:31] offset0:77 offset1:78
	v_cvt_pk_bf16_f32 v28, v56, v57
	v_cvt_pk_bf16_f32 v29, v54, v55
	v_cvt_pk_bf16_f32 v30, v44, v45
	v_cvt_pk_bf16_f32 v31, v58, v59
	v_mov_b32_e32 v1, v0
	ds_write2st64_b64 v179, v[28:29], v[30:31] offset0:79 offset1:80
	v_mov_b64_e32 v[46:47], v[2:3]
	v_mov_b64_e32 v[102:103], v[2:3]
	v_mov_b64_e32 v[30:31], v[2:3]
	v_mov_b64_e32 v[34:35], v[2:3]
	v_mov_b64_e32 v[38:39], v[2:3]
	v_mov_b64_e32 v[42:43], v[2:3]
	v_mov_b64_e32 v[70:71], v[2:3]
	v_mov_b64_e32 v[82:83], v[2:3]
	v_mov_b64_e32 v[90:91], v[2:3]
	v_mov_b64_e32 v[94:95], v[2:3]
	v_mov_b32_e32 v187, 0xf149f2ca
	v_mov_b64_e32 v[44:45], v[0:1]
	v_mov_b64_e32 v[100:101], v[0:1]
	v_mov_b64_e32 v[28:29], v[0:1]
	v_mov_b64_e32 v[32:33], v[0:1]
	v_mov_b64_e32 v[36:37], v[0:1]
	v_mov_b64_e32 v[40:41], v[0:1]
	v_mov_b64_e32 v[68:69], v[0:1]
	v_mov_b64_e32 v[80:81], v[0:1]
	v_mov_b64_e32 v[88:89], v[0:1]
	v_mov_b64_e32 v[92:93], v[0:1]
	v_mov_b32_e32 v1, 0xf149f2ca
	s_branch .LBB0_1339
.Lfp15_dispatch:
	s_nop 3
	s_cmp_gt_i32 s14, 63
	s_cbranch_scc1 .Lfp15_win
	s_cmp_eq_u32 s14, s45
	s_cbranch_scc0 .Lfp15_body
	s_branch .LBB0_1338
.Lfp15_win:
	s_lshl_b32 s8, s14, 6
	s_add_i32 s8, s8, 0xfffff000
	s_or_b32 s9, s8, 63
	s_cmp_gt_i32 s9, s44
	s_cbranch_scc1 .LBB0_1338
	s_cmp_lt_i32 s8, s82
	s_cbranch_scc0 .Lfp15_body

; __device__ __forceinline__ void nsa_qk(f32x4 (&s)[2][4], const u16* sK, const bf16x8 (&qf)[2][2], int fr, int fq) {
; #pragma unroll
;   for (int mt = 0; mt < 4; ++mt) {
;     s[0][mt] = (f32x4){0.f, 0.f, 0.f, 0.f}; s[1][mt] = (f32x4){0.f, 0.f, 0.f, 0.f};
; #pragma unroll
;     for (int ks = 0; ks < 2; ++ks) {
;       bf16x8 kf = *(const bf16x8*)(sK + (mt * 16 + fr) * LDSP + ks * 32 + fq * 8);
;       s[0][mt] = mfma16(kf, qf[0][ks], s[0][mt]);
;       s[1][mt] = mfma16(kf, qf[1][ks], s[1][mt]);
;     }
;   }
; }
; __device__ __forceinline__ void phase_nsa_sw(const Params& p, u16* sm) {
;     ...
;       nsa_qk(s, cK, qf, fr, fq);
;       {
;         const bool is_sel = (v < 64);
;         const int kt = is_sel ? v : v - 64;
;         const bool lv = is_sel ? (bool)((mymask >> v) & 1ull) : true;
;         const bool masked = is_sel ? (v == (t0 >> 6)) : !((64 * kt + 63 <= t0) && (64 * kt >= t0 - 480));
;         if (masked) {
.LBB0_1339:
	s_add_i32 s8, s89, 0xffffff80
	s_and_b32 s16, s8, 0x80
	s_mulk_i32 s16, 0x48
	s_and_b32 s8, s8, 0x100
	s_mulk_i32 s8, 0x90
	s_add_i32 s16, s16, s8
	v_lshl_add_u32 v2, s16, 1, v218
	ds_read_b128 v[48:51], v2
	ds_read_b128 v[52:55], v2 offset:64
	s_cmp_gt_i32 s14, 63
	s_cselect_b64 s[8:9], -1, 0
	s_mov_b64 s[10:11], -1
	s_waitcnt lgkmcnt(1)
	v_mfma_f32_16x16x32_bf16 v[56:59], v[48:51], v[4:7], 0
	s_and_b64 vcc, exec, s[8:9]
	v_mfma_f32_16x16x32_bf16 v[48:51], v[48:51], v[12:15], 0
	s_waitcnt lgkmcnt(0)
	v_mfma_f32_16x16x32_bf16 v[124:127], v[52:55], v[8:11], v[56:59]
	v_mfma_f32_16x16x32_bf16 v[72:75], v[52:55], v[16:19], v[48:51]
	s_nop 4
	ds_read_b128 v[48:51], v2 offset:2304
	ds_read_b128 v[52:55], v2 offset:2368
	s_waitcnt lgkmcnt(1)
	v_mfma_f32_16x16x32_bf16 v[56:59], v[48:51], v[4:7], 0
	v_mfma_f32_16x16x32_bf16 v[48:51], v[48:51], v[12:15], 0
	s_waitcnt lgkmcnt(0)
	v_mfma_f32_16x16x32_bf16 v[128:131], v[52:55], v[8:11], v[56:59]
	v_mfma_f32_16x16x32_bf16 v[76:79], v[52:55], v[16:19], v[48:51]
	s_nop 4
	ds_read_b128 v[48:51], v2 offset:4608
	ds_read_b128 v[52:55], v2 offset:4672
	s_waitcnt lgkmcnt(1)
	v_mfma_f32_16x16x32_bf16 v[56:59], v[48:51], v[4:7], 0
	v_mfma_f32_16x16x32_bf16 v[48:51], v[48:51], v[12:15], 0
	s_waitcnt lgkmcnt(0)
	v_mfma_f32_16x16x32_bf16 v[136:139], v[52:55], v[8:11], v[56:59]
	v_mfma_f32_16x16x32_bf16 v[84:87], v[52:55], v[16:19], v[48:51]
	s_nop 4
	ds_read_b128 v[48:51], v2 offset:6912
	ds_read_b128 v[52:55], v2 offset:6976
	s_waitcnt lgkmcnt(1)
	v_mfma_f32_16x16x32_bf16 v[56:59], v[48:51], v[4:7], 0
	v_mfma_f32_16x16x32_bf16 v[48:51], v[48:51], v[12:15], 0
	s_waitcnt lgkmcnt(0)
	v_mfma_f32_16x16x32_bf16 v[120:123], v[52:55], v[8:11], v[56:59]
	v_mfma_f32_16x16x32_bf16 v[96:99], v[52:55], v[16:19], v[48:51]
	s_cbranch_vccnz .LBB0_1341
	s_cmp_eq_u32 s14, s45
	s_mov_b64 s[10:11], 0
	s_cselect_b64 s[12:13], -1, 0

; #define NSA_FETCH(rk, rv, e) do { const int v_ = lst[(e)]; \
;       const u16* kp_ = (v_ < 64) ? ksb + (size_t)v_ * 64 * 128 : kwb + (size_t)(v_ - 64) * 64 * 128; \
;       const u16* vp_ = (v_ < 64) ? vsb + v_ * 64 : vwb + (v_ - 64) * 64; \
;       rk = *(const uint4*)(kp_ + (size_t)pr * 128 + pc * 8); rv = *(const uint4*)(vp_ + (size_t)pr * SEQ + pc * 8); } while (0)
; #define NSA_PUT(rk, rv, buf) do { *(uint4*)(sK + (buf) * 2 * 64 * LDSP + prl * LDSP + pc * 8) = rk; \
;       *(uint4*)(sV + (buf) * 2 * 64 * LDSP + pr * LDSP + pc * 8) = rv; } while (0)
; __device__ __forceinline__ void phase_nsa_sw(const Params& p, u16* sm) {
;     ...
;       if (i + 1 < ntl) NSA_PUT(rkA, rvA, (i + 1) & 1);
;       if (i + 2 < ntl) NSA_FETCH(rkA, rvA, i + 2);
.LBB0_1349:
	s_branch .Lfp15_tail_orig

; __device__ __forceinline__ void nsa_qk(f32x4 (&s)[2][4], const u16* sK, const bf16x8 (&qf)[2][2], int fr, int fq) {
; #pragma unroll
;   for (int mt = 0; mt < 4; ++mt) {
;     s[0][mt] = (f32x4){0.f, 0.f, 0.f, 0.f}; s[1][mt] = (f32x4){0.f, 0.f, 0.f, 0.f};
; #pragma unroll
;     for (int ks = 0; ks < 2; ++ks) {
;       bf16x8 kf = *(const bf16x8*)(sK + (mt * 16 + fr) * LDSP + ks * 32 + fq * 8);
;       s[0][mt] = mfma16(kf, qf[0][ks], s[0][mt]);
;       s[1][mt] = mfma16(kf, qf[1][ks], s[1][mt]);
;     }
;   }
; }
; __device__ __forceinline__ void nsa_pv(f32x4 (&acc)[2][4], const u16* sV, const bf16x8 (&pf)[2][2], int fr, int fq) {
; #pragma unroll
;   for (int k2 = 0; k2 < 2; ++k2)
; #pragma unroll
;     for (int dm = 0; dm < 4; ++dm) {
;       bf16x8 vf = *(const bf16x8*)(sV + (dm * 16 + fr) * LDSP + k2 * 32 + fq * 8);
;       acc[0][dm] = mfma16(vf, pf[0][k2], acc[0][dm]);
;       acc[1][dm] = mfma16(vf, pf[1][k2], acc[1][dm]);
;     }
; }
; template <bool MASKED>
; __device__ __forceinline__ void nsa_online_step(NsaState& st, f32x4 (&s)[2][4], unsigned vmask, bool lanevalid, const u16* sV, int fr, int fq) {
;   bf16x8 pf[2][2];
;   const uint32_t lmask = lanevalid ? 0xffffffffu : 0u;
;   const bf16x8 ones = mk_frag(0x3F803F80u, 0x3F803F80u, 0x3F803F80u, 0x3F803F80u);
;   constexpr float DEFER = 8.f / SM_C;
; #pragma unroll
;   for (int hh = 0; hh < 2; ++hh) {
;     float tmax = -1e30f;
;     if (MASKED) {
; #pragma unroll
;       for (int mt = 0; mt < 4; ++mt)
; #pragma unroll
;         for (int j = 0; j < 4; ++j) {
;           const float sc = ((vmask >> (mt * 4 + j)) & 1u) ? s[hh][mt][j] : -1e30f;
;           s[hh][mt][j] = sc;
;           tmax = fmaxf(tmax, sc);
;         }
;     } else {
; #pragma unroll
;       for (int mt = 0; mt < 4; ++mt)
; #pragma unroll
;         for (int j = 0; j < 4; ++j) tmax = fmaxf(tmax, s[hh][mt][j]);
;       tmax = lanevalid ? tmax : -1e30f;
;     }
;     tmax = fmaxf(tmax, __shfl_xor(tmax, 16));
;     tmax = fmaxf(tmax, __shfl_xor(tmax, 32));
;     const bool upd = tmax > st.m[hh] + DEFER;
;     if (__ballot(upd) != 0ull) {
; __device__ __forceinline__ void phase_nsa_sw(const Params& p, u16* sm) {
;     ...
;       if (i + 1 < ntl) NSA_PUT(rkA, rvA, (i + 1) & 1);
;       if (i + 2 < ntl) NSA_FETCH(rkA, rvA, i + 2);
;     }
.Lfp15_tail_orig:
	s_add_i32 s10, s42, 1
	v_cmp_ge_i32_e64 s[8:9], s10, v231
	v_readfirstlane_b32 s13, v231
	s_add_i32 s11, s42, 3
	s_and_b32 s12, s11, 1
	s_mulk_i32 s12, 0x4800
	s_and_b32 s18, s11, 2
	s_mul_i32 s18, s18, 0x9000
	s_add_i32 s12, s12, s18
	s_add_i32 s13, s13, -1
	s_min_i32 s11, s11, s13
	v_readlane_b32 s18, v24, s11
	v_readlane_b32 s19, v25, s11
	s_cmp_lt_u32 s11, 64
	s_cselect_b32 s11, s18, s19
	s_cmp_lt_i32 s11, 64
	s_cselect_b32 s14, s62, s78
	s_cselect_b32 s15, s63, s79
	s_cselect_b32 s16, s66, s80
	s_cselect_b32 s17, s67, s81
	s_and_b32 s13, s11, 63
	s_lshl_b32 s18, s13, 14
	s_lshl_b32 s13, s13, 7
	s_add_u32 s14, s14, s18
	s_addc_u32 s15, s15, 0
	s_add_u32 s16, s16, s13
	s_addc_u32 s17, s17, 0
	v_readfirstlane_b32 s18, v251
	v_readfirstlane_b32 s19, v252
	s_nop 0
	s_add_u32 s18, s18, s12
	s_mov_b32 m0, s18
	s_add_u32 s18, s18, 0x2400
	global_load_lds_dwordx4 v248, s[14:15]
	s_mov_b32 m0, s18
	s_cmp_ge_u32 s19, 0x2400
	global_load_lds_dwordx4 v249, s[16:17]
	s_cselect_b32 s14, s16, s14
	s_cselect_b32 s15, s17, s15
	s_add_u32 s19, s19, s12
	s_mov_b32 m0, s19
	s_mov_b64 exec, 0xffff
	global_load_lds_dwordx4 v250, s[14:15]
	s_mov_b64 exec, -1
	s_add_i32 s83, s83, 4
	s_addk_i32 s89, 0x80
	s_and_b64 vcc, exec, s[8:9]
	s_cbranch_vccnz .LBB0_1323
	s_mov_b32 s42, s10
	s_branch .LBB0_1336
.Lfp15_tail:
	s_add_i32 s10, s42, 1
	v_cmp_ge_i32_e64 s[8:9], s10, v231
	v_readfirstlane_b32 s13, v231
	s_add_i32 s11, s42, 3
	s_and_b32 s12, s11, 1
	s_mulk_i32 s12, 0x4800
	s_and_b32 s18, s11, 2
	s_mul_i32 s18, s18, 0x9000
	s_add_i32 s12, s12, s18
	s_add_i32 s13, s13, -1
	s_min_i32 s11, s11, s13
	v_readlane_b32 s18, v24, s11
	v_readlane_b32 s19, v25, s11
	s_cmp_lt_u32 s11, 64
	s_cselect_b32 s11, s18, s19
	s_cmp_lt_i32 s11, 64
	s_cselect_b32 s14, s62, s78
	s_cselect_b32 s15, s63, s79
	s_cselect_b32 s16, s66, s80
	s_cselect_b32 s17, s67, s81
	s_and_b32 s13, s11, 63
	s_lshl_b32 s18, s13, 14
	s_lshl_b32 s13, s13, 7
	s_add_u32 s14, s14, s18
	s_addc_u32 s15, s15, 0
	s_add_u32 s16, s16, s13
	s_addc_u32 s17, s17, 0
	v_readfirstlane_b32 s18, v251
	v_readfirstlane_b32 s19, v252
	s_nop 0
	s_add_u32 s18, s18, s12
	s_mov_b32 m0, s18
	s_add_u32 s18, s18, 0x2400
	global_load_lds_dwordx4 v248, s[14:15]
	s_mov_b32 m0, s18
	s_cmp_ge_u32 s19, 0x2400
	global_load_lds_dwordx4 v249, s[16:17]
	s_cselect_b32 s14, s16, s14
	s_cselect_b32 s15, s17, s15
	s_add_u32 s19, s19, s12
	s_mov_b32 m0, s19
	s_mov_b64 exec, 0xffff
	global_load_lds_dwordx4 v250, s[14:15]
	s_mov_b64 exec, -1
	s_add_i32 s83, s83, 4
	s_addk_i32 s89, 0x80
	s_and_b64 vcc, exec, s[8:9]
	s_cbranch_vccnz .LBB0_1323
	s_mov_b32 s42, s10
	v_readfirstlane_b32 s11, v192
	s_nop 3
	s_cmp_lt_u32 s11, 0x100
	s_cbranch_scc1 .LBB0_1336
	v_readlane_b32 s14, v24, s42
	v_readlane_b32 s15, v25, s42
	v_cmp_ne_u32_e32 vcc, s42, v203
	s_cmp_lt_u32 s42, 64
	s_cselect_b32 s14, s14, s15
	s_cbranch_vccz .Lfp15_park
	s_branch .Lfp15_dispatch
.Lfp15_body:
	s_add_i32 s8, s89, 0xffffff80
	s_and_b32 s9, s8, 0x100
	s_and_b32 s8, s8, 0x80
	s_mulk_i32 s8, 0x90
	s_mulk_i32 s9, 0x120
	s_add_i32 s8, s8, s9
	v_add_u32_e32 v2, s8, v218
	s_cmp_gt_i32 s14, 63
	ds_read_b128 v[136:139], v2
	ds_read_b128 v[140:143], v2 offset:64
	ds_read_b128 v[144:147], v2 offset:2304
	ds_read_b128 v[148:151], v2 offset:2368
	ds_read_b128 v[152:155], v2 offset:4608
	ds_read_b128 v[156:159], v2 offset:4672
	ds_read_b128 v[160:163], v2 offset:6912
	ds_read_b128 v[164:167], v2 offset:6976
	s_cbranch_scc1 .Lfp15_lvall
	s_lshl_b64 s[10:11], 1, s14
	v_and_b32_e32 v1, s10, v210
	v_and_b32_e32 v3, s11, v211
	v_or_b32_e32 v1, v1, v3
	v_cmp_ne_u32_e32 vcc, 0, v1
	s_mov_b64 s[30:31], vcc
	s_branch .Lfp15_lvdone
.Lfp15_lvall:
	s_mov_b64 s[30:31], -1
.Lfp15_lvdone:
	s_mov_b32 s10, 0x3e38aa3b
	s_waitcnt lgkmcnt(4)
	v_mfma_f32_16x16x32_bf16 v[68:71], v[136:139], v[4:7], 0
	v_mfma_f32_16x16x32_bf16 v[72:75], v[144:147], v[4:7], 0
	v_mfma_f32_16x16x32_bf16 v[68:71], v[140:143], v[8:11], v[68:71]
	v_mfma_f32_16x16x32_bf16 v[72:75], v[148:151], v[8:11], v[72:75]
	s_waitcnt lgkmcnt(0)
	ds_read_b128 v[28:31], v2 offset:9216
	ds_read_b128 v[36:39], v2 offset:11520
	ds_read_b128 v[44:47], v2 offset:13824
	ds_read_b128 v[124:127], v2 offset:16128
	ds_read_b128 v[32:35], v2 offset:9280
	ds_read_b128 v[40:43], v2 offset:11584
	ds_read_b128 v[120:123], v2 offset:13888
	ds_read_b128 v[128:131], v2 offset:16192
	v_mfma_f32_16x16x32_bf16 v[76:79], v[152:155], v[4:7], 0
	v_mfma_f32_16x16x32_bf16 v[80:83], v[160:163], v[4:7], 0
	v_mfma_f32_16x16x32_bf16 v[76:79], v[156:159], v[8:11], v[76:79]
	v_mfma_f32_16x16x32_bf16 v[80:83], v[164:167], v[8:11], v[80:83]
	v_mfma_f32_16x16x32_bf16 v[84:87], v[136:139], v[12:15], 0
	v_mfma_f32_16x16x32_bf16 v[88:91], v[144:147], v[12:15], 0
	v_mfma_f32_16x16x32_bf16 v[84:87], v[140:143], v[16:19], v[84:87]
	v_mfma_f32_16x16x32_bf16 v[88:91], v[148:151], v[16:19], v[88:91]
	v_max3_f32 v1, v68, v69, v70
	v_mfma_f32_16x16x32_bf16 v[92:95], v[152:155], v[12:15], 0
	v_max3_f32 v1, v1, v71, v72
	v_max3_f32 v1, v1, v73, v74
	v_mfma_f32_16x16x32_bf16 v[96:99], v[160:163], v[12:15], 0
	v_max3_f32 v1, v1, v75, v76
	v_max3_f32 v1, v1, v77, v78
	v_mfma_f32_16x16x32_bf16 v[92:95], v[156:159], v[16:19], v[92:95]
	v_max3_f32 v1, v1, v79, v80
	v_max3_f32 v1, v1, v81, v82
	v_mfma_f32_16x16x32_bf16 v[96:99], v[164:167], v[16:19], v[96:99]
	v_max_f32_e32 v1, v1, v83
	v_add_f32_e32 v168, 0x42317218, v234
	v_cmp_gt_f32_e32 vcc, v1, v168
	s_and_b64 s[8:9], vcc, s[30:31]
	s_cbranch_scc1 .Lfp15_upd0
; template <bool MASKED>
; __device__ __forceinline__ void nsa_online_step(NsaState& st, f32x4 (&s)[2][4], unsigned vmask, bool lanevalid, const u16* sV, int fr, int fq) {
;     ...
;   for (int hh = 0; hh < 2; ++hh) {
;     float tmax = -1e30f;
;     if (MASKED) {
; #pragma unroll
;       for (int mt = 0; mt < 4; ++mt)
; #pragma unroll
;         for (int j = 0; j < 4; ++j) {
;           const float sc = ((vmask >> (mt * 4 + j)) & 1u) ? s[hh][mt][j] : -1e30f;
;           s[hh][mt][j] = sc;
;           tmax = fmaxf(tmax, sc);
;         }
;     } else {
; #pragma unroll
;       for (int mt = 0; mt < 4; ++mt)
; #pragma unroll
;         for (int j = 0; j < 4; ++j) tmax = fmaxf(tmax, s[hh][mt][j]);
;       tmax = lanevalid ? tmax : -1e30f;
;     }
;     tmax = fmaxf(tmax, __shfl_xor(tmax, 16));
;     tmax = fmaxf(tmax, __shfl_xor(tmax, 32));
;     const bool upd = tmax > st.m[hh] + DEFER;
;     if (__ballot(upd) != 0ull) {
;       const float mnew = upd ? tmax : st.m[hh];
;       const float alpha = __builtin_amdgcn_exp2f((st.m[hh] - mnew) * SM_C);
;       st.m[hh] = mnew;
; #pragma unroll
;       for (int dm = 0; dm < 4; ++dm) st.acc[hh][dm] *= alpha;
;       st.accL[hh] *= alpha;
;     }
;     const float nb = -st.m[hh] * SM_C;
; #pragma unroll
;     for (int k2 = 0; k2 < 2; ++k2) {
;       uint32_t pw[4];
; #pragma unroll
;       for (int e2 = 0; e2 < 4; ++e2) {
;         const int mt = 2 * k2 + (e2 >> 1), j = (e2 & 1) * 2;
;         float p0 = __builtin_amdgcn_exp2f(__builtin_fmaf(s[hh][mt][j], SM_C, nb));
;         float p1 = __builtin_amdgcn_exp2f(__builtin_fmaf(s[hh][mt][j + 1], SM_C, nb));
;         if (MASKED) {
;           p0 = ((vmask >> (mt * 4 + j)) & 1u) ? p0 : 0.f;
;           p1 = ((vmask >> (mt * 4 + j + 1)) & 1u) ? p1 : 0.f;
;         }
;         pw[e2] = pack2(p0, p1);
;         if (!MASKED) pw[e2] &= lmask;
;       }
;       pf[hh][k2] = mk_frag(pw[0], pw[1], pw[2], pw[3]);
;       st.accL[hh] = mfma16(ones, pf[hh][k2], st.accL[hh]);
;     }
; #pragma unroll
;     for (int k2 = 0; k2 < 2; ++k2)
; #pragma unroll
;       for (int dm = 0; dm < 4; ++dm) {
;         const bf16x8 vf = *(const bf16x8*)(sV + (dm * 16 + fr) * LDSP + k2 * 32 + fq * 8);
;         st.acc[hh][dm] = mfma16(vf, pf[hh][k2], st.acc[hh][dm]);
;       }
.Lfp15_noupd0:
	v_mul_f32_e32 v2, 0xbe38aa3b, v234
	v_cndmask_b32_e64 v2, v221, v2, s[30:31]
	v_pk_fma_f32 v[136:137], v[68:69], s[10:11], v[2:3] op_sel_hi:[1,0,0]
	v_pk_fma_f32 v[138:139], v[70:71], s[10:11], v[2:3] op_sel_hi:[1,0,0]
	v_exp_f32_e32 v136, v136
	v_exp_f32_e32 v137, v137
	v_exp_f32_e32 v138, v138
	v_exp_f32_e32 v139, v139
	v_pk_fma_f32 v[140:141], v[72:73], s[10:11], v[2:3] op_sel_hi:[1,0,0]
	v_pk_fma_f32 v[142:143], v[74:75], s[10:11], v[2:3] op_sel_hi:[1,0,0]
	v_cvt_pk_bf16_f32 v236, v136, v137
	v_cvt_pk_bf16_f32 v237, v138, v139
	v_exp_f32_e32 v140, v140
	v_exp_f32_e32 v141, v141
	v_exp_f32_e32 v142, v142
	v_exp_f32_e32 v143, v143
	v_pk_fma_f32 v[144:145], v[76:77], s[10:11], v[2:3] op_sel_hi:[1,0,0]
	v_pk_fma_f32 v[146:147], v[78:79], s[10:11], v[2:3] op_sel_hi:[1,0,0]
	v_cvt_pk_bf16_f32 v238, v140, v141
	v_cvt_pk_bf16_f32 v239, v142, v143
	v_exp_f32_e32 v144, v144
	v_exp_f32_e32 v145, v145
	v_exp_f32_e32 v146, v146
	v_exp_f32_e32 v147, v147
	v_pk_fma_f32 v[148:149], v[80:81], s[10:11], v[2:3] op_sel_hi:[1,0,0]
	v_pk_fma_f32 v[150:151], v[82:83], s[10:11], v[2:3] op_sel_hi:[1,0,0]
	v_cvt_pk_bf16_f32 v240, v144, v145
	v_cvt_pk_bf16_f32 v241, v146, v147
	v_exp_f32_e32 v148, v148
	v_exp_f32_e32 v149, v149
	v_exp_f32_e32 v150, v150
	v_exp_f32_e32 v151, v151
.Lfp15_xend:
	v_readfirstlane_b32 s8, v192
	v_cvt_pk_bf16_f32 v242, v148, v149
	v_cvt_pk_bf16_f32 v243, v150, v151
	s_cmp_lt_u32 s8, 0x100
	s_cbranch_scc1 .Lfp15_ystart
	s_waitcnt vmcnt(3)
	s_waitcnt lgkmcnt(0)
	s_barrier
.Lfp15_ystart:
	s_waitcnt lgkmcnt(0)
	v_max3_f32 v1, v84, v85, v86
	v_max3_f32 v1, v1, v87, v88
	v_mfma_f32_16x16x32_bf16 v[48:51], v[20:23], v[236:239], v[48:51]
	v_max3_f32 v1, v1, v89, v90
	v_max3_f32 v1, v1, v91, v92
	v_mfma_f32_16x16x32_bf16 v[52:55], v[28:31], v[236:239], v[52:55]
	v_max3_f32 v1, v1, v93, v94
	v_max3_f32 v1, v1, v95, v96
	v_mfma_f32_16x16x32_bf16 v[56:59], v[36:39], v[236:239], v[56:59]
	v_max3_f32 v1, v1, v97, v98
	v_max_f32_e32 v1, v1, v99
	v_mfma_f32_16x16x32_bf16 v[60:63], v[44:47], v[236:239], v[60:63]
	v_mfma_f32_16x16x32_bf16 v[64:67], v[124:127], v[236:239], v[64:67]
	v_add_f32_e32 v168, 0x42317218, v235
	v_cmp_gt_f32_e32 vcc, v1, v168
	s_and_b64 s[8:9], vcc, s[30:31]
	s_cbranch_scc1 .Lfp15_upd1
.Lfp15_noupd1:
	v_mul_f32_e32 v2, 0xbe38aa3b, v235
	v_cndmask_b32_e64 v2, v221, v2, s[30:31]
	v_pk_fma_f32 v[136:137], v[84:85], s[10:11], v[2:3] op_sel_hi:[1,0,0]
	v_pk_fma_f32 v[138:139], v[86:87], s[10:11], v[2:3] op_sel_hi:[1,0,0]
	v_exp_f32_e32 v136, v136
	v_exp_f32_e32 v137, v137
	v_exp_f32_e32 v138, v138
	v_mfma_f32_16x16x32_bf16 v[48:51], v[20:23], v[240:243], v[48:51]
	v_exp_f32_e32 v139, v139
	v_pk_fma_f32 v[140:141], v[88:89], s[10:11], v[2:3] op_sel_hi:[1,0,0]
	v_pk_fma_f32 v[142:143], v[90:91], s[10:11], v[2:3] op_sel_hi:[1,0,0]
	v_cvt_pk_bf16_f32 v244, v136, v137
	v_cvt_pk_bf16_f32 v245, v138, v139
	v_mfma_f32_16x16x32_bf16 v[52:55], v[32:35], v[240:243], v[52:55]
	v_exp_f32_e32 v140, v140
	v_exp_f32_e32 v141, v141
	v_exp_f32_e32 v142, v142
	v_exp_f32_e32 v143, v143
	v_pk_fma_f32 v[144:145], v[92:93], s[10:11], v[2:3] op_sel_hi:[1,0,0]
	v_mfma_f32_16x16x32_bf16 v[56:59], v[40:43], v[240:243], v[56:59]
	v_pk_fma_f32 v[146:147], v[94:95], s[10:11], v[2:3] op_sel_hi:[1,0,0]
	v_cvt_pk_bf16_f32 v246, v140, v141
	v_cvt_pk_bf16_f32 v247, v142, v143
	v_exp_f32_e32 v144, v144
	v_exp_f32_e32 v145, v145
	v_mfma_f32_16x16x32_bf16 v[60:63], v[120:123], v[240:243], v[60:63]
	v_exp_f32_e32 v146, v146
	v_exp_f32_e32 v147, v147
	v_pk_fma_f32 v[148:149], v[96:97], s[10:11], v[2:3] op_sel_hi:[1,0,0]
	v_pk_fma_f32 v[150:151], v[98:99], s[10:11], v[2:3] op_sel_hi:[1,0,0]
	v_cvt_pk_bf16_f32 v100, v144, v145
	v_mfma_f32_16x16x32_bf16 v[64:67], v[128:131], v[240:243], v[64:67]
	v_cvt_pk_bf16_f32 v101, v146, v147
	v_exp_f32_e32 v148, v148
	v_exp_f32_e32 v149, v149
	v_exp_f32_e32 v150, v150
	v_exp_f32_e32 v151, v151
	s_nop 0
	v_cvt_pk_bf16_f32 v102, v148, v149
	v_cvt_pk_bf16_f32 v103, v150, v151
	s_nop 0
	v_mfma_f32_16x16x32_bf16 v[132:135], v[20:23], v[244:247], v[132:135]
	v_mfma_f32_16x16x32_bf16 v[116:119], v[28:31], v[244:247], v[116:119]
	v_mfma_f32_16x16x32_bf16 v[112:115], v[36:39], v[244:247], v[112:115]
	v_mfma_f32_16x16x32_bf16 v[108:111], v[44:47], v[244:247], v[108:111]
	v_mfma_f32_16x16x32_bf16 v[104:107], v[124:127], v[244:247], v[104:107]
	v_mfma_f32_16x16x32_bf16 v[132:135], v[20:23], v[100:103], v[132:135]
	v_mfma_f32_16x16x32_bf16 v[116:119], v[32:35], v[100:103], v[116:119]
	v_mfma_f32_16x16x32_bf16 v[112:115], v[40:43], v[100:103], v[112:115]
	v_mfma_f32_16x16x32_bf16 v[108:111], v[120:123], v[100:103], v[108:111]
	v_mfma_f32_16x16x32_bf16 v[104:107], v[128:131], v[100:103], v[104:107]
	s_branch .Lfp15_tail
.Lfp15_upd0:
	v_cndmask_b32_e64 v1, v221, v1, s[30:31]
	v_mov_b32_e32 v3, v1
	s_nop 1
	v_permlane16_swap_b32_e32 v1, v3
	s_nop 0
	v_max_f32_e32 v1, v1, v3
	v_mov_b32_e32 v3, v1
	s_nop 1
	v_permlane32_swap_b32_e32 v1, v3
	s_nop 0
	v_max_f32_e32 v1, v1, v3
	v_cmp_gt_f32_e32 vcc, v1, v168
	s_nop 1
	v_cndmask_b32_e32 v3, v234, v1, vcc
	v_sub_f32_e32 v1, v234, v3
	v_mul_f32_e32 v168, 0x3e38aa3b, v1
	v_exp_f32_e32 v168, v168
	v_mov_b32_e32 v234, v3
	s_nop 0
	v_pk_mul_f32 v[48:49], v[48:49], v[168:169] op_sel_hi:[1,0]
	v_pk_mul_f32 v[50:51], v[50:51], v[168:169] op_sel_hi:[1,0]
	v_pk_mul_f32 v[52:53], v[52:53], v[168:169] op_sel_hi:[1,0]
	v_pk_mul_f32 v[54:55], v[54:55], v[168:169] op_sel_hi:[1,0]
	v_pk_mul_f32 v[56:57], v[56:57], v[168:169] op_sel_hi:[1,0]
	v_pk_mul_f32 v[58:59], v[58:59], v[168:169] op_sel_hi:[1,0]
	v_pk_mul_f32 v[60:61], v[60:61], v[168:169] op_sel_hi:[1,0]
	v_pk_mul_f32 v[62:63], v[62:63], v[168:169] op_sel_hi:[1,0]
	v_pk_mul_f32 v[64:65], v[64:65], v[168:169] op_sel_hi:[1,0]
	v_pk_mul_f32 v[66:67], v[66:67], v[168:169] op_sel_hi:[1,0]
	s_branch .Lfp15_noupd0
.Lfp15_upd1:
	v_cndmask_b32_e64 v1, v221, v1, s[30:31]
	v_mov_b32_e32 v3, v1
	s_nop 1
	v_permlane16_swap_b32_e32 v1, v3
	s_nop 0
	v_max_f32_e32 v1, v1, v3
	v_mov_b32_e32 v3, v1
	s_nop 1
	v_permlane32_swap_b32_e32 v1, v3
	s_nop 0
	v_max_f32_e32 v1, v1, v3
	v_cmp_gt_f32_e32 vcc, v1, v168
	s_nop 1
	v_cndmask_b32_e32 v3, v235, v1, vcc
	v_sub_f32_e32 v1, v235, v3
	v_mul_f32_e32 v168, 0x3e38aa3b, v1
	v_exp_f32_e32 v168, v168
	v_mov_b32_e32 v235, v3
	s_nop 0
	v_pk_mul_f32 v[132:133], v[132:133], v[168:169] op_sel_hi:[1,0]
	v_pk_mul_f32 v[134:135], v[134:135], v[168:169] op_sel_hi:[1,0]
	v_pk_mul_f32 v[116:117], v[116:117], v[168:169] op_sel_hi:[1,0]
	v_pk_mul_f32 v[118:119], v[118:119], v[168:169] op_sel_hi:[1,0]
	v_pk_mul_f32 v[112:113], v[112:113], v[168:169] op_sel_hi:[1,0]
	v_pk_mul_f32 v[114:115], v[114:115], v[168:169] op_sel_hi:[1,0]
	v_pk_mul_f32 v[108:109], v[108:109], v[168:169] op_sel_hi:[1,0]
	v_pk_mul_f32 v[110:111], v[110:111], v[168:169] op_sel_hi:[1,0]
	v_pk_mul_f32 v[104:105], v[104:105], v[168:169] op_sel_hi:[1,0]
	v_pk_mul_f32 v[106:107], v[106:107], v[168:169] op_sel_hi:[1,0]
	s_branch .Lfp15_noupd1
